# P0: odd workgroups walk their item list in reverse (LayerNorm rows first, weight transposes last) so latency-bound transposes and bandwidth-bound LN rows overlap across workgroups
# baseline (speedup 1.0000x reference)
; __global__ void __launch_bounds__(512, 2) fwd_mega(Params P) {
;     ...
;     {
;     for (int base = bid * 2; base < 1984 + 4096; base += nblk * 2) {
;         PHASE_IDS
;         const int it = base + team;
.LBB0_17:
	v_writelane_b32 v255, s12, 19
	s_load_dwordx16 s[44:59], s[0:1], 0x40
	s_lshl_b32 s86, s33, 1
	v_writelane_b32 v255, s13, 20
	v_writelane_b32 v255, s14, 21
	v_writelane_b32 v255, s15, 22
	v_writelane_b32 v255, s16, 23
	v_writelane_b32 v255, s17, 24
	v_writelane_b32 v255, s18, 25
	v_writelane_b32 v255, s19, 26
	s_cmpk_gt_i32 s33, 0xbdf
	s_cbranch_scc1 .LBB0_40
	s_and_b32 s16, s96, 0xffffffc0
	s_add_u32 s0, s80, 0x9000000
	s_addc_u32 s1, s81, 0
	s_add_u32 s2, s80, 0x1c80000
	s_addc_u32 s3, s81, 0
	s_add_u32 s4, s80, 0xf800000
	s_addc_u32 s5, s81, 0
	s_add_u32 s6, s80, 0x1200000
	s_addc_u32 s7, s81, 0
	s_lshl_b32 s17, s82, 1
	s_mov_b32 s18, 0x12c00
	s_movk_i32 s19, 0x3bf
	s_movk_i32 s20, 0x7bf
	v_mov_b32_e32 v17, 0
	v_mov_b32_e32 v18, 0x3727c5ac
	s_mov_b32 s21, 0x800000
	s_movk_i32 s22, 0xfc
	s_mov_b32 s23, 0x88888889
	s_movk_i32 s24, 0x7ff
	s_movk_i32 s25, 0xdff
	s_movk_i32 s26, 0xe07
	s_movk_i32 s27, 0xe10
	s_movk_i32 s28, 0x3840
	v_mov_b32_e32 v19, 2
	v_mov_b32_e32 v20, 4
	s_mov_b32 s29, s86
	s_bitcmp1_b32 s33, 0
	s_cbranch_scc0 .LBB0_22
.Lp0_seek:
	s_add_i32 s98, s29, s17
	s_cmp_le_i32 s98, 0x17bf
	s_cbranch_scc0 .Lp0_seek_done
	s_mov_b32 s29, s98
	s_branch .Lp0_seek
.Lp0_seek_done:
	s_sub_i32 s17, 0, s17
	s_branch .LBB0_22

; __global__ void __launch_bounds__(512, 2) fwd_mega(Params P) {
;     ...
;     for (int base = bid * 2; base < 1984 + 4096; base += nblk * 2) {
;         PHASE_IDS
;         const int it = base + team;
;         if (it < 960) {
.LBB0_21:
	s_or_b64 exec, exec, s[8:9]
	s_add_i32 s29, s29, s17
	s_cmp_gt_u32 s29, 0x17bf
	s_cbranch_scc1 .LBB0_40
